# NA V^T stored in key-row-blocked layout [head][grid row][d][64 tok] by the in-projection epilogue: each key-row V^T stage is one contiguous 8 KB DMA
# speedup vs baseline: 1.0088x; 1.0019x over previous
.LBB0_245:
	s_or_b64 exec, exec, s[0:1]
	v_readlane_b32 s0, v252, 34
	v_readlane_b32 s1, v252, 35
	s_and_b64 s[0:1], s[0:1], s[50:51]
	s_ashr_i32 s3, s38, 6
	s_and_b32 s2, 0xffff, s34
	s_cmp_lg_u32 s2, 0
	s_cselect_b64 s[14:15], -1, 0
	s_cmp_lg_u64 s[14:15], 0
	v_readlane_b32 s2, v252, 37
	s_addc_u32 s2, s2, 0
	s_mul_hi_i32 s2, s2, 0x2aaaaaab
	s_lshr_b32 s12, s2, 31
	s_add_i32 s2, s2, s12
	s_ashr_i32 s12, s2, 31
	s_abs_i32 s2, s2
	v_cvt_f32_u32_e32 v0, s2
	v_readlane_b32 s13, v253, 58
	s_xor_b32 s77, s13, s12
	s_sub_i32 s13, 0, s2
	v_rcp_iflag_f32_e32 v0, v0
	v_readlane_b32 s18, v253, 59
	s_mov_b64 s[60:61], s[50:51]
	v_readlane_b32 s23, v252, 36
	v_mul_f32_e32 v0, 0x4f7ffffe, v0
	v_cvt_u32_f32_e32 v0, v0
	v_and_b32_e32 v139, 15, v138
	v_mov_b64_e32 v[2:3], s[8:9]
	v_readlane_b32 s46, v252, 38
	v_readfirstlane_b32 s16, v0
	s_mul_i32 s13, s13, s16
	s_mul_hi_u32 s13, s16, s13
	s_add_i32 s16, s16, s13
	s_mul_hi_u32 s13, s18, s16
	s_mul_i32 s17, s13, s2
	s_sub_i32 s17, s18, s17
	s_add_i32 s18, s13, 1
	s_sub_i32 s19, s17, s2
	s_cmp_ge_u32 s17, s2
	s_cselect_b32 s13, s18, s13
	s_cselect_b32 s17, s19, s17
	s_add_i32 s18, s13, 1
	s_cmp_ge_u32 s17, s2
	s_cselect_b32 s13, s18, s13
	s_xor_b32 s78, s13, s77
	v_readlane_b32 s13, v253, 61
	v_readlane_b32 s17, v253, 60
	s_xor_b32 s12, s13, s12
	s_mul_hi_u32 s13, s17, s16
	s_mul_i32 s16, s13, s2
	s_sub_i32 s16, s17, s16
	s_sub_i32 s22, s78, s77
	s_add_i32 s17, s13, 1
	s_sub_i32 s18, s16, s2
	s_cmp_ge_u32 s16, s2
	s_cselect_b32 s13, s17, s13
	s_cselect_b32 s16, s18, s16
	s_add_i32 s17, s13, 1
	s_cmp_ge_u32 s16, s2
	s_cselect_b32 s2, s17, s13
	s_xor_b32 s2, s2, s12
	s_sub_i32 s2, s2, s12
	s_sub_i32 s12, s2, s22
	s_lshl_b32 s13, s3, 4
	s_lshl_b32 s12, s12, 2
	s_and_b32 s34, s13, 48
	s_cmp_eq_u32 s3, s12
	s_cselect_b64 s[16:17], -1, 0
	s_ashr_i32 s79, s38, 8
	s_and_b64 s[50:51], s[0:1], s[16:17]
	s_add_i32 s92, s22, s79
	s_cmp_lt_i32 s3, s12
	s_cselect_b64 s[16:17], -1, 0
	s_and_b64 s[18:19], s[16:17], exec
	s_cselect_b32 s13, s92, s22
	s_lshl_b32 s13, s13, 6
	s_or_b32 s13, s13, s34
	s_and_b64 s[18:19], s[50:51], exec
	s_cselect_b32 s13, s23, s13
	v_or_b32_e32 v0, s13, v139
	v_mad_i64_i32 v[4:5], s[18:19], v0, s57, v[2:3]
	v_readlane_b32 s47, v252, 39
	v_and_b32_e32 v0, 48, v138
	s_mov_b64 s[48:49], 0xc404200
	v_lshl_add_u64 v[4:5], v[4:5], 0, s[46:47]
	v_lshl_add_u64 v[4:5], v[4:5], 0, v[0:1]
	s_mov_b32 s39, 0xc404000
	v_lshl_add_u64 v[6:7], v[4:5], 0, s[48:49]
	v_add_co_u32_e32 v4, vcc, s39, v4
	s_add_i32 s13, s3, 8
	s_nop 0
	v_addc_co_u32_e32 v5, vcc, 0, v5, vcc
	global_load_dwordx4 v[52:55], v[4:5], off offset:512
	global_load_dwordx4 v[56:59], v[6:7], off offset:64
	s_cmp_eq_u32 s13, s12
	s_cselect_b64 s[18:19], -1, 0
	s_ashr_i32 s80, s13, 2
	s_and_b64 s[68:69], s[0:1], s[18:19]
	s_add_i32 s55, s80, s22
	s_cmp_lt_i32 s13, s12
	s_cselect_b64 s[18:19], -1, 0
	s_and_b64 s[40:41], s[18:19], exec
	s_cselect_b32 s13, s55, s22
	s_lshl_b32 s13, s13, 6
	s_or_b32 s13, s13, s34
	s_and_b64 s[40:41], s[68:69], exec
	s_cselect_b32 s13, s23, s13
	v_or_b32_e32 v4, s13, v139
	v_mad_i64_i32 v[4:5], s[40:41], v4, s57, v[2:3]
	v_lshl_add_u64 v[4:5], v[4:5], 0, s[46:47]
	v_lshl_add_u64 v[4:5], v[4:5], 0, v[0:1]
	v_lshl_add_u64 v[6:7], v[4:5], 0, s[48:49]
	v_add_co_u32_e32 v4, vcc, s39, v4
	s_add_i32 s13, s3, 16
	s_nop 0
	v_addc_co_u32_e32 v5, vcc, 0, v5, vcc
	s_cmp_eq_u32 s13, s12
	s_cselect_b64 s[40:41], -1, 0
	s_ashr_i32 s81, s13, 2
	s_and_b64 s[66:67], s[0:1], s[40:41]
	s_add_i32 s54, s81, s22
	s_cmp_lt_i32 s13, s12
	s_cselect_b64 s[40:41], -1, 0
	s_and_b64 s[42:43], s[40:41], exec
	s_cselect_b32 s13, s54, s22
	s_lshl_b32 s13, s13, 6
	s_or_b32 s13, s13, s34
	s_and_b64 s[42:43], s[66:67], exec
	s_cselect_b32 s13, s23, s13
	v_and_b32_e32 v22, 63, v138
	v_lshl_or_b32 v23, s3, 8, v22
	v_and_b32_e32 v27, 31, v138
	v_bfe_u32 v157, v138, 4, 2
	v_and_b32_e32 v164, 3, v138
	v_lshlrev_b32_e32 v163, 1, v139
	v_bitop3_b32 v158, v157, v138, 3 bitop3:0x78
	v_bitop3_b32 v159, v157, v164, 4 bitop3:0x36
	global_load_dwordx4 v[60:63], v[4:5], off offset:512
	global_load_dwordx4 v[64:67], v[6:7], off offset:64
	v_or_b32_e32 v4, s13, v139
	v_mad_i64_i32 v[4:5], s[42:43], v4, s57, v[2:3]
	v_lshl_add_u64 v[4:5], v[4:5], 0, s[46:47]
	v_lshl_add_u64 v[4:5], v[4:5], 0, v[0:1]
	v_lshl_add_u64 v[8:9], v[4:5], 0, s[48:49]
	v_add_co_u32_e32 v4, vcc, s39, v4
	s_add_i32 s13, s3, 24
	s_nop 0
	v_addc_co_u32_e32 v5, vcc, 0, v5, vcc
	s_cmp_eq_u32 s13, s12
	s_cselect_b64 s[42:43], -1, 0
	s_ashr_i32 s82, s13, 2
	s_and_b64 s[64:65], s[0:1], s[42:43]
	s_add_i32 s35, s82, s22
	s_cmp_lt_i32 s13, s12
	s_cselect_b64 s[52:53], -1, 0
	s_and_b64 s[0:1], s[52:53], exec
	s_cselect_b32 s0, s35, s22
	s_lshl_b32 s0, s0, 6
	s_or_b32 s12, s0, s34
	s_and_b64 s[0:1], s[64:65], exec
	s_cselect_b32 s0, s23, s12
	v_or_b32_e32 v12, s0, v139
	v_mad_i64_i32 v[2:3], s[0:1], v12, s57, v[2:3]
	v_lshl_add_u64 v[2:3], v[2:3], 0, s[46:47]
	v_lshl_add_u64 v[2:3], v[2:3], 0, v[0:1]
	v_lshl_add_u64 v[16:17], v[2:3], 0, s[48:49]
	v_add_co_u32_e32 v2, vcc, s39, v2
	v_readlane_b32 s0, v252, 40
	s_nop 0
	v_addc_co_u32_e32 v3, vcc, 0, v3, vcc
	v_ashrrev_i32_e32 v0, 3, v23
	v_readlane_b32 s1, v252, 41
	v_xor_b32_e32 v24, v0, v138
	v_add_u32_e32 v0, 0x4000, v0
	s_lshl_b32 s12, s3, 2
	s_or_b32 s13, s12, 2
	s_mov_b64 s[46:47], 0x200000
	global_load_dwordx4 v[4:7], v[4:5], off offset:512
	s_nop 0
	global_load_dwordx4 v[8:11], v[8:9], off offset:64
	global_load_dwordx4 v[12:15], v[2:3], off offset:512
	s_nop 0
	global_load_dwordx4 v[16:19], v[16:17], off offset:64
	v_mov_b64_e32 v[2:3], s[0:1]
	v_mad_i64_i32 v[20:21], s[0:1], v0, s57, v[2:3]
	v_lshlrev_b32_e32 v0, 4, v24
	s_or_b32 s1, s12, 1
	v_and_b32_e32 v0, 0x70, v0
	s_lshl_b32 s0, s3, 12
	v_lshl_or_b32 v24, s1, 6, v22
	v_lshl_add_u64 v[20:21], v[20:21], 0, v[0:1]
	s_add_i32 s0, s0, 0
	v_ashrrev_i32_e32 v0, 3, v24
	s_mov_b32 m0, s0
	v_xor_b32_e32 v25, v0, v138
	v_add_u32_e32 v0, 0x4000, v0
	s_lshl_b32 s1, s1, 10
	s_add_i32 s1, s1, 0
	s_or_b32 s12, s12, 3
	s_lshl_b32 s3, s3, 10
	global_load_lds_dwordx4 v[20:21], off
	v_mad_i64_i32 v[20:21], s[42:43], v0, s57, v[2:3]
	v_lshlrev_b32_e32 v0, 4, v25
	v_and_b32_e32 v0, 0x70, v0
	v_lshl_or_b32 v25, s13, 6, v22
	v_lshl_add_u64 v[20:21], v[20:21], 0, v[0:1]
	v_ashrrev_i32_e32 v0, 3, v25
	s_mov_b32 m0, s1
	v_xor_b32_e32 v26, v0, v138
	v_add_u32_e32 v0, 0x4000, v0
	global_load_lds_dwordx4 v[20:21], off
	v_mad_i64_i32 v[20:21], s[42:43], v0, s57, v[2:3]
	v_lshlrev_b32_e32 v0, 4, v26
	v_and_b32_e32 v0, 0x70, v0
	s_lshl_b32 s13, s13, 10
	v_lshl_or_b32 v26, s12, 6, v22
	v_lshl_add_u64 v[20:21], v[20:21], 0, v[0:1]
	s_add_i32 s23, s13, 0
	v_ashrrev_i32_e32 v0, 3, v26
	s_mov_b32 m0, s23
	v_xor_b32_e32 v22, v0, v138
	v_add_u32_e32 v0, 0x4000, v0
	global_load_lds_dwordx4 v[20:21], off
	v_mad_i64_i32 v[20:21], s[42:43], v0, s57, v[2:3]
	v_lshlrev_b32_e32 v0, 4, v22
	s_lshl_b32 s12, s12, 10
	v_and_b32_e32 v0, 0x70, v0
	s_add_i32 s39, s12, 0
	v_readlane_b32 s12, v252, 44
	v_lshl_add_u64 v[20:21], v[20:21], 0, v[0:1]
	s_mov_b32 m0, s39
	v_ashrrev_i32_e32 v0, 5, v23
	v_readlane_b32 s13, v252, 45
	global_load_lds_dwordx4 v[20:21], off
	v_bitop3_b32 v28, v0, v27, 1 bitop3:0x6c
	v_mov_b64_e32 v[20:21], s[12:13]
	s_movk_i32 s12, 0x80
	v_mad_i64_i32 v[22:23], s[42:43], v0, s12, v[20:21]
	v_lshlrev_b32_e32 v0, 4, v28
	v_and_b32_e32 v247, 0x180, v0
	v_and_b32_e32 v0, 0x70, v0
	v_lshl_or_b32 v0, v247, 6, v0
	v_lshl_add_u64 v[22:23], v[22:23], 0, v[0:1]
	v_ashrrev_i32_e32 v0, 5, v24
	v_lshl_add_u64 v[22:23], v[22:23], 0, s[46:47]
	s_add_i32 m0, s0, 0x8000
	v_bitop3_b32 v24, v0, v27, 3 bitop3:0x6c
	global_load_lds_dwordx4 v[22:23], off
	v_mad_i64_i32 v[22:23], s[42:43], v0, s12, v[20:21]
	v_lshlrev_b32_e32 v0, 4, v24
	v_and_b32_e32 v247, 0x180, v0
	v_and_b32_e32 v0, 0x70, v0
	v_lshl_or_b32 v0, v247, 6, v0
	v_lshl_add_u64 v[22:23], v[22:23], 0, v[0:1]
	v_ashrrev_i32_e32 v0, 5, v25
	v_lshl_add_u64 v[22:23], v[22:23], 0, s[46:47]
	s_add_i32 m0, s1, 0x8000
	v_bitop3_b32 v24, v0, v27, 5 bitop3:0x6c
	global_load_lds_dwordx4 v[22:23], off
	v_mad_i64_i32 v[22:23], s[0:1], v0, s12, v[20:21]
	v_lshlrev_b32_e32 v0, 4, v24
	v_and_b32_e32 v247, 0x180, v0
	v_and_b32_e32 v0, 0x70, v0
	v_lshl_or_b32 v0, v247, 6, v0
	v_lshl_add_u64 v[22:23], v[22:23], 0, v[0:1]
	v_ashrrev_i32_e32 v0, 5, v26
	v_lshl_add_u64 v[22:23], v[22:23], 0, s[46:47]
	s_add_i32 m0, s23, 0x8000
	v_bitop3_b32 v24, v0, v27, 7 bitop3:0x6c
	global_load_lds_dwordx4 v[22:23], off
	v_mad_i64_i32 v[22:23], s[0:1], v0, s12, v[20:21]
	v_lshlrev_b32_e32 v0, 4, v24
	v_and_b32_e32 v247, 0x180, v0
	v_and_b32_e32 v0, 0x70, v0
	v_lshl_or_b32 v0, v247, 6, v0
	v_lshl_add_u64 v[22:23], v[22:23], 0, v[0:1]
	v_bfrev_b32_e32 v0, -0.5
	v_med3_i32 v0, s2, 5, v0
	s_movk_i32 s1, 0xffc0
	v_readfirstlane_b32 s2, v0
	v_mov_b32_e32 v0, s38
	v_lshl_add_u64 v[22:23], v[22:23], 0, s[46:47]
	s_add_i32 m0, s39, 0x8000
	v_bfi_b32 v0, s1, v0, v138
	global_load_lds_dwordx4 v[22:23], off
	v_ashrrev_i32_e32 v23, 3, v0
	v_xor_b32_e32 v0, v23, v138
	v_lshlrev_b32_e32 v0, 4, v0
	v_med3_i32 v22, s22, 4, v216
	v_mad_i64_i32 v[2:3], s[22:23], v23, s57, v[2:3]
	v_and_b32_e32 v0, 0x70, v0
	v_readfirstlane_b32 s83, v22
	v_lshl_add_u64 v[76:77], v[2:3], 0, v[0:1]
	v_mad_i64_i32 v[2:3], s[22:23], v23, s12, v[20:21]
	s_add_i32 s0, s83, -4
	s_add_i32 s2, s2, 2
	v_readlane_b32 s22, v254, 38
	s_min_u32 s12, s0, s2
	v_readlane_b32 s23, v254, 39
	s_mul_i32 s22, s12, 0x5c000
	s_mov_b32 s13, s23
	v_lshl_add_u64 v[78:79], v[2:3], 0, v[0:1]
	v_lshl_add_u64 v[2:3], v[76:77], 0, s[22:23]
	s_add_i32 s1, s3, 0
	s_lshl_b32 s22, s12, 13
	v_writelane_b32 v254, s12, 38
	v_add_u32_e32 v0, -3, v22
	s_add_i32 m0, s1, 0x10000
	v_writelane_b32 v254, s13, 39
	v_min_u32_e32 v20, s2, v0
	s_mov_b32 s12, 0x5c000
	global_load_lds_dwordx4 v[2:3], off
	v_lshl_add_u64 v[2:3], v[78:79], 0, s[22:23]
	s_add_i32 m0, s1, 0x12000
	v_mul_lo_u32 v0, v20, s12
	global_load_lds_dwordx4 v[2:3], off
	v_lshl_add_u64 v[2:3], v[76:77], 0, v[0:1]
	s_add_i32 m0, s1, 0x14000
	v_lshlrev_b32_e32 v0, 13, v20
	global_load_lds_dwordx4 v[2:3], off
	v_lshl_add_u64 v[2:3], v[78:79], 0, v[0:1]
	v_add_u32_e32 v0, -2, v22
	v_min_u32_e32 v20, s2, v0
	s_add_i32 m0, s1, 0x16000
	v_mul_lo_u32 v0, v20, s12
	global_load_lds_dwordx4 v[2:3], off
	v_lshl_add_u64 v[2:3], v[76:77], 0, v[0:1]
	s_add_i32 m0, s1, 0x18000
	v_lshlrev_b32_e32 v0, 13, v20
	global_load_lds_dwordx4 v[2:3], off
	v_lshl_add_u64 v[2:3], v[78:79], 0, v[0:1]
	s_add_i32 m0, s1, 0x1a000
	s_cmp_le_u32 s0, s2
	global_load_lds_dwordx4 v[2:3], off
	s_cbranch_scc0 .LBB0_320
	v_med3_u32 v2, s34, 8, 40
	v_add_u32_e32 v3, -8, v2
	v_and_b32_e32 v22, 24, v163
	v_or_b32_e32 v23, v3, v164
	v_add_u32_e32 v22, v23, v22
	v_or_b32_e32 v23, 4, v157
	v_lshlrev_b32_e32 v80, 7, v22
	v_or_b32_e32 v22, 4, v22
	v_lshlrev_b32_e32 v0, 3, v157
	v_or_b32_e32 v20, s34, v139
	v_lshlrev_b32_e32 v83, 7, v22
	v_bitop3_b32 v24, v22, v157, 7 bitop3:0x6c
	v_bitop3_b32 v22, v22, v23, 7 bitop3:0x6c
	v_med3_u32 v20, v20, 8, 56
	v_lshlrev_b32_e32 v117, 4, v22
	v_add_u32_e32 v22, v3, v0
	v_lshrrev_b32_e32 v3, 3, v3
	v_add_u32_e32 v21, -8, v20
	v_add_u32_e32 v20, 8, v20
	v_add_u32_e32 v3, v3, v157
	v_cmp_ge_u32_e32 vcc, v22, v21
	v_cmp_lt_u32_e64 s[0:1], v22, v20
	v_or_b32_e32 v23, 1, v22
	v_bitop3_b32 v3, v3, v138, 7 bitop3:0x78
	s_and_b64 s[22:23], vcc, s[0:1]
	v_cmp_ge_u32_e32 vcc, v23, v21
	v_cmp_lt_u32_e64 s[0:1], v23, v20
	v_or_b32_e32 v23, 2, v22
	v_lshlrev_b32_e32 v119, 4, v3
	v_med3_i32 v3, s92, 4, v216
	s_and_b64 s[38:39], vcc, s[0:1]
	v_cmp_ge_u32_e32 vcc, v23, v21
	v_cmp_lt_u32_e64 s[0:1], v23, v20
	v_or_b32_e32 v23, 3, v22
	v_add_u32_e32 v120, -4, v3
	v_add_u32_e32 v121, 4, v3
	v_med3_i32 v3, s55, 4, v216
	s_and_b64 s[48:49], vcc, s[0:1]
	v_cmp_ge_u32_e32 vcc, v23, v21
	v_cmp_lt_u32_e64 s[0:1], v23, v20
	v_or_b32_e32 v23, 4, v22
	v_add_u32_e32 v122, -4, v3
	v_add_u32_e32 v123, 4, v3
	v_med3_i32 v3, s54, 4, v216
	s_and_b64 s[58:59], vcc, s[0:1]
	v_cmp_ge_u32_e32 vcc, v23, v21
	v_cmp_lt_u32_e64 s[0:1], v23, v20
	v_or_b32_e32 v23, 5, v22
	v_add_u32_e32 v124, -4, v3
	v_add_u32_e32 v125, 4, v3
	v_med3_i32 v3, s35, 4, v216
	s_and_b64 s[96:97], vcc, s[0:1]
	v_cmp_ge_u32_e32 vcc, v23, v21
	v_cmp_lt_u32_e64 s[0:1], v23, v20
	v_or_b32_e32 v23, 6, v22
	v_add_u32_e32 v126, -4, v3
	v_add_u32_e32 v127, 4, v3
	v_add3_u32 v3, v2, -1, v0
	s_and_b64 s[42:43], vcc, s[0:1]
	v_cmp_ge_u32_e32 vcc, v23, v21
	v_cmp_lt_u32_e64 s[0:1], v23, v20
	v_or_b32_e32 v23, 7, v22
	v_sub_u32_e32 v3, v3, v139
	s_and_b64 s[44:45], vcc, s[0:1]
	v_cmp_ge_u32_e32 vcc, v23, v21
	v_cmp_lt_u32_e64 s[0:1], v23, v20
	v_subrev_u32_e32 v3, s34, v3
	s_and_b64 s[46:47], vcc, s[0:1]
	v_med3_i32 v3, v3, -15, 15
	s_add_i32 s0, s78, s82
	v_lshlrev_b32_e32 v3, 2, v3
	s_mulk_i32 s0, 0x7c
	v_subrev_u32_e32 v20, s0, v3
	v_readlane_b32 s1, v254, 35
	v_lshlrev_b32_e32 v116, 4, v24
	s_add_i32 s77, s77, s83
	v_add_u32_e32 v128, s1, v20
	v_add3_u32 v20, v2, -2, v0
	v_sub_u32_e32 v20, v20, v139
	v_subrev_u32_e32 v20, s34, v20
	v_med3_i32 v20, v20, -15, 15
	v_lshlrev_b32_e32 v20, 2, v20
	v_subrev_u32_e32 v21, s0, v20
	v_add_u32_e32 v129, s1, v21
	v_add3_u32 v21, v2, -3, v0
	v_sub_u32_e32 v21, v21, v139
	v_subrev_u32_e32 v21, s34, v21
	v_med3_i32 v21, v21, -15, 15
	v_lshlrev_b32_e32 v21, 2, v21
	v_subrev_u32_e32 v23, s0, v21
	v_add_u32_e32 v130, s1, v23
	v_add3_u32 v23, v2, -4, v0
	v_sub_u32_e32 v23, v23, v139
	v_subrev_u32_e32 v23, s34, v23
	v_med3_i32 v23, v23, -15, 15
	v_lshlrev_b32_e32 v23, 2, v23
	v_subrev_u32_e32 v24, s0, v23
	v_add_u32_e32 v131, s1, v24
	v_add3_u32 v24, v2, -5, v0
	v_sub_u32_e32 v24, v24, v139
	v_subrev_u32_e32 v24, s34, v24
	v_med3_i32 v24, v24, -15, 15
	v_lshlrev_b32_e32 v24, 2, v24
	v_subrev_u32_e32 v25, s0, v24
	v_add_u32_e32 v132, s1, v25
	v_add3_u32 v25, v2, -6, v0
	v_add3_u32 v0, v2, -7, v0
	v_sub_u32_e32 v0, v0, v139
	v_subrev_u32_e32 v0, s34, v0
	v_med3_i32 v0, v0, -15, 15
	v_lshlrev_b32_e32 v0, 2, v0
	v_subrev_u32_e32 v2, s0, v0
	v_sub_u32_e32 v25, v25, v139
	v_add_u32_e32 v134, s1, v2
	v_sub_u32_e32 v2, v22, v139
	v_subrev_u32_e32 v25, s34, v25
	v_subrev_u32_e32 v2, s34, v2
	v_med3_i32 v25, v25, -15, 15
	v_med3_i32 v2, v2, -15, 15
	v_lshlrev_b32_e32 v25, 2, v25
	v_lshlrev_b32_e32 v2, 2, v2
	v_subrev_u32_e32 v26, s0, v25
	v_subrev_u32_e32 v22, s0, v2
	s_add_i32 s0, s78, s81
	s_mulk_i32 s0, 0x7c
	v_add_u32_e32 v135, s1, v22
	v_subrev_u32_e32 v22, s0, v3
	v_add_u32_e32 v142, s1, v22
	v_subrev_u32_e32 v22, s0, v20
	v_add_u32_e32 v143, s1, v22
	v_subrev_u32_e32 v22, s0, v21
	v_add_u32_e32 v144, s1, v22
	v_subrev_u32_e32 v22, s0, v23
	v_add_u32_e32 v145, s1, v22
	v_subrev_u32_e32 v22, s0, v24
	v_add_u32_e32 v146, s1, v22
	v_subrev_u32_e32 v22, s0, v25
	v_add_u32_e32 v147, s1, v22
	v_subrev_u32_e32 v22, s0, v0
	v_add_u32_e32 v148, s1, v22
	v_subrev_u32_e32 v22, s0, v2
	s_add_i32 s0, s78, s80
	s_mulk_i32 s0, 0x7c
	v_add_u32_e32 v149, s1, v22
	v_subrev_u32_e32 v22, s0, v3
	v_add_u32_e32 v150, s1, v22
	v_subrev_u32_e32 v22, s0, v20
	v_add_u32_e32 v151, s1, v22
	v_subrev_u32_e32 v22, s0, v21
	v_add_u32_e32 v152, s1, v22
	v_subrev_u32_e32 v22, s0, v23
	v_add_u32_e32 v153, s1, v22
	v_subrev_u32_e32 v22, s0, v24
	v_add_u32_e32 v154, s1, v22
	v_subrev_u32_e32 v22, s0, v25
	v_add_u32_e32 v155, s1, v22
	v_subrev_u32_e32 v22, s0, v0
	v_add_u32_e32 v162, s1, v22
	v_subrev_u32_e32 v22, s0, v2
	s_add_i32 s0, s78, s79
	s_mulk_i32 s0, 0x7c
	v_subrev_u32_e32 v3, s0, v3
	v_add_u32_e32 v168, s1, v3
	v_subrev_u32_e32 v3, s0, v20
	v_add_u32_e32 v169, s1, v3
	v_subrev_u32_e32 v3, s0, v21
	v_add_u32_e32 v170, s1, v3
	v_subrev_u32_e32 v3, s0, v23
	v_add_u32_e32 v171, s1, v3
	v_subrev_u32_e32 v3, s0, v24
	v_add_u32_e32 v172, s1, v3
	v_subrev_u32_e32 v3, s0, v25
	v_subrev_u32_e32 v0, s0, v0
	v_add_u32_e32 v173, s1, v3
	v_add_u32_e32 v174, s1, v0
	v_subrev_u32_e32 v0, s0, v2
	v_mov_b32_e32 v2, v1
	v_mov_b32_e32 v3, v1
	v_add_u32_e32 v133, s1, v26
	v_add_u32_e32 v167, s1, v22
	v_add_u32_e32 v175, s1, v0
	v_mov_b32_e32 v0, v1
	v_mov_b64_e32 v[86:87], v[2:3]
	v_mov_b64_e32 v[90:91], v[2:3]
	v_mov_b64_e32 v[94:95], v[2:3]
	v_mov_b64_e32 v[98:99], v[2:3]
	v_mov_b64_e32 v[114:115], v[2:3]
	v_mov_b64_e32 v[110:111], v[2:3]
	v_mov_b64_e32 v[106:107], v[2:3]
	v_mov_b64_e32 v[102:103], v[2:3]
	v_mov_b64_e32 v[22:23], v[2:3]
	v_mov_b64_e32 v[26:27], v[2:3]
	v_mov_b64_e32 v[34:35], v[2:3]
	v_mov_b64_e32 v[46:47], v[2:3]
	v_mov_b64_e32 v[30:31], v[2:3]
	v_mov_b64_e32 v[38:39], v[2:3]
	v_mov_b64_e32 v[42:43], v[2:3]
	v_mov_b64_e32 v[50:51], v[2:3]
	v_lshlrev_b32_e32 v81, 4, v158
	v_lshlrev_b32_e32 v82, 4, v159
	v_lshlrev_b32_e32 v118, 7, v139
	s_mulk_i32 s77, 0x7c
	s_add_i32 s79, s83, -5
	s_mov_b32 s78, 0
	v_mov_b32_e32 v165, 0xf149f2ca
	v_mov_b32_e32 v141, 0
	v_mov_b64_e32 v[84:85], v[0:1]
	v_mov_b64_e32 v[88:89], v[0:1]
	v_mov_b64_e32 v[92:93], v[0:1]
	v_mov_b64_e32 v[96:97], v[0:1]
	v_mov_b64_e32 v[112:113], v[0:1]
	v_mov_b64_e32 v[108:109], v[0:1]
	v_mov_b64_e32 v[104:105], v[0:1]
	v_mov_b64_e32 v[100:101], v[0:1]
	v_mov_b32_e32 v166, 0xf149f2ca
	v_mov_b32_e32 v140, 0
	v_mov_b64_e32 v[20:21], v[0:1]
	v_mov_b64_e32 v[24:25], v[0:1]
	v_mov_b64_e32 v[32:33], v[0:1]
	v_mov_b64_e32 v[44:45], v[0:1]
	v_mov_b32_e32 v161, 0xf149f2ca
	v_mov_b32_e32 v137, 0
	v_mov_b64_e32 v[28:29], v[0:1]
	v_mov_b64_e32 v[36:37], v[0:1]
	v_mov_b64_e32 v[40:41], v[0:1]
	v_mov_b64_e32 v[48:49], v[0:1]
	v_mov_b32_e32 v160, 0xf149f2ca
	v_mov_b32_e32 v136, 0
	v_mov_b32_e32 v0, 0
	v_mov_b32_e32 v177, 0xf149f2ca
	v_mov_b32_e32 v2, 0
	v_mov_b32_e32 v178, 0xf149f2ca
	v_mov_b32_e32 v3, 0
	v_mov_b32_e32 v179, 0xf149f2ca
	v_mov_b32_e32 v176, 0
	v_mov_b32_e32 v180, 0xf149f2ca
	s_branch .LBB0_249

.LBB0_249:
	s_add_i32 s0, s79, 4
	s_min_i32 s12, s0, s2
	v_mov_b32_e32 v68, 0x5c000
	v_mad_i64_i32 v[68:69], s[0:1], s12, v68, v[76:77]
	s_add_i32 s0, s78, 0xc000
	s_and_b32 s0, s0, 0xc000
	s_add_i32 s0, s0, 0
	s_add_i32 s13, s0, s3
	s_lshl_b32 s0, s12, 12
	s_waitcnt vmcnt(4)
	s_barrier
	s_add_i32 m0, s13, 0x10000
	s_ashr_i32 s1, s0, 31
	global_load_lds_dwordx4 v[68:69], off
	v_lshl_add_u64 v[68:69], s[0:1], 1, v[78:79]
	s_add_i32 m0, s13, 0x12000
	s_add_i32 s79, s79, 1
	global_load_lds_dwordx4 v[68:69], off
	s_and_b32 s12, s78, 0xc000
	v_cmp_ge_u32_e32 vcc, s79, v120
	s_add_i32 s80, s12, 0
	v_cmp_lt_u32_e64 s[0:1], s79, v121
	s_and_b64 s[82:83], s[16:17], vcc
	s_add_i32 s80, s80, 0x10000
	s_and_b64 s[0:1], s[82:83], s[0:1]
	v_add_u32_e32 v68, s80, v80
	v_add_u32_e32 v69, s80, v83
	s_andn2_b64 vcc, exec, s[0:1]
	v_add_u32_e32 v183, v68, v81
	v_add_u32_e32 v184, v68, v82
	v_add_u32_e32 v181, v69, v116
	v_add_u32_e32 v182, v69, v117
	s_cbranch_vccnz .LBB0_267
	ds_read_b128 v[68:71], v183
	ds_read_b128 v[72:75], v184
	ds_read_b128 v[198:201], v181
	ds_read_b128 v[186:189], v182
	v_add_u32_e32 v190, s77, v175
	ds_read_b32 v190, v190
	v_add_u32_e32 v191, s77, v174
	ds_read_b32 v191, v191
	v_add_u32_e32 v192, s77, v173
	ds_read_b32 v192, v192
	v_add_u32_e32 v193, s77, v172
	ds_read_b32 v193, v193
	v_add_u32_e32 v194, s77, v171
	ds_read_b32 v194, v194
	v_add_u32_e32 v195, s77, v170
	ds_read_b32 v195, v195
	v_add_u32_e32 v196, s77, v169
	ds_read_b32 v196, v196
	v_add_u32_e32 v197, s77, v168
	ds_read_b32 v197, v197
	v_add3_u32 v246, s80, v118, v119
	v_mov_b32_e32 v141, 0xf149f2ca
	v_mov_b32_e32 v185, 0xf149f2ca
	s_waitcnt lgkmcnt(10)
	v_mfma_f32_16x16x32_bf16 v[68:71], v[68:71], v[52:55], 0
	s_waitcnt lgkmcnt(8)
	v_mfma_f32_16x16x32_bf16 v[198:201], v[198:201], v[52:55], 0
	v_mfma_f32_16x16x32_bf16 v[72:75], v[72:75], v[56:59], v[68:71]
	v_mfma_f32_16x16x32_bf16 v[198:201], v[186:189], v[56:59], v[198:201]
	ds_read_b128 v[226:229], v246 offset:8192
	ds_read_b128 v[230:233], v246 offset:10240
	ds_read_b128 v[234:237], v246 offset:12288
	ds_read_b128 v[242:245], v246 offset:14336
	s_waitcnt lgkmcnt(4)
	s_nop 1
	v_add_f32_e32 v190, v72, v190
	v_cndmask_b32_e64 v185, v185, v190, s[22:23]
	v_add_f32_e32 v191, v73, v191
	v_cndmask_b32_e64 v141, v141, v191, s[38:39]
	v_mov_b32_e32 v72, 0xf149f2ca
	v_mov_b32_e32 v186, 0xf149f2ca
	v_add_f32_e32 v192, v74, v192
	v_cndmask_b32_e64 v186, v186, v192, s[48:49]
	v_add_f32_e32 v193, v75, v193
	v_cndmask_b32_e64 v72, v72, v193, s[58:59]
	v_mov_b32_e32 v73, 0xf149f2ca
	v_mov_b32_e32 v74, 0xf149f2ca
	v_add_f32_e32 v194, v198, v194
	v_cndmask_b32_e64 v74, v74, v194, s[96:97]
	v_add_f32_e32 v195, v199, v195
	v_cndmask_b32_e64 v73, v73, v195, s[42:43]
	v_mov_b32_e32 v68, 0xf149f2ca
	v_mov_b32_e32 v69, 0xf149f2ca
	v_add_f32_e32 v196, v200, v196
	v_cndmask_b32_e64 v69, v69, v196, s[44:45]
	v_add_f32_e32 v197, v201, v197
	v_cndmask_b32_e64 v68, v68, v197, s[46:47]
	v_max3_f32 v70, v141, v185, v72
	v_max3_f32 v71, v186, v68, v69
	v_max3_f32 v75, v74, v73, v71
	v_max_f32_e32 v70, v70, v75
	v_mov_b32_e32 v71, v70
	s_nop 1
	v_permlane16_swap_b32_e32 v70, v71
	v_max_f32_e32 v70, v70, v71
	v_mov_b32_e32 v71, v70
	s_nop 1
	v_permlane32_swap_b32_e32 v70, v71
	v_max3_f32 v165, v180, v70, v71
	v_sub_f32_e32 v71, v185, v165
	v_exp_f32_e32 v71, v71
	v_sub_f32_e32 v141, v141, v165
	v_exp_f32_e32 v185, v141
	v_sub_f32_e32 v141, v186, v165
	v_exp_f32_e32 v186, v141
	v_sub_f32_e32 v72, v72, v165
	v_exp_f32_e32 v72, v72
	v_sub_f32_e32 v74, v74, v165
	v_add_f32_e32 v75, 0, v71
	v_exp_f32_e32 v74, v74
	v_sub_f32_e32 v73, v73, v165
	v_add_f32_e32 v75, v185, v75
	v_exp_f32_e32 v73, v73
	v_sub_f32_e32 v69, v69, v165
	v_add_f32_e32 v75, v186, v75
	v_exp_f32_e32 v187, v69
	v_add_f32_e32 v75, v72, v75
	v_add_f32_e32 v75, v74, v75
	v_add_f32_e32 v75, v73, v75
	v_sub_f32_e32 v68, v68, v165
	v_sub_f32_e32 v70, v180, v165
	v_add_f32_e32 v69, v187, v75
	v_exp_f32_e32 v75, v68
	v_exp_f32_e32 v180, v70
	v_cvt_pk_bf16_f32 v68, v71, v185
	v_cvt_pk_bf16_f32 v70, v74, v73
	v_add_f32_e32 v141, v75, v69
	v_fmac_f32_e32 v141, v176, v180
	v_cvt_pk_bf16_f32 v69, v186, v72
	v_cvt_pk_bf16_f32 v71, v187, v75
	v_pk_mul_f32 v[102:103], v[102:103], v[180:181] op_sel_hi:[1,0]
	v_pk_mul_f32 v[100:101], v[100:101], v[180:181] op_sel_hi:[1,0]
	v_pk_mul_f32 v[106:107], v[106:107], v[180:181] op_sel_hi:[1,0]
	v_pk_mul_f32 v[104:105], v[104:105], v[180:181] op_sel_hi:[1,0]
	s_waitcnt lgkmcnt(0)
	v_mfma_f32_16x16x32_bf16 v[100:103], v[226:229], v[68:71], v[100:103]
	v_pk_mul_f32 v[110:111], v[110:111], v[180:181] op_sel_hi:[1,0]
	v_pk_mul_f32 v[108:109], v[108:109], v[180:181] op_sel_hi:[1,0]
	v_mfma_f32_16x16x32_bf16 v[104:107], v[230:233], v[68:71], v[104:107]
	v_pk_mul_f32 v[114:115], v[114:115], v[180:181] op_sel_hi:[1,0]
	v_pk_mul_f32 v[112:113], v[112:113], v[180:181] op_sel_hi:[1,0]
	v_mfma_f32_16x16x32_bf16 v[108:111], v[234:237], v[68:71], v[108:111]
	v_mov_b32_e32 v180, v165
	v_mov_b32_e32 v176, v141
	v_mfma_f32_16x16x32_bf16 v[112:115], v[242:245], v[68:71], v[112:115]

.Lip0_V:
	s_cmpk_lt_u32 s0, 0x180
	s_cbranch_scc0 .Lip0_RV
	s_lshr_b32 s12, s0, 6
	s_mul_i32 s12, s12, 0x208000
	s_and_b32 s15, s0, 63
	s_lshl_b32 s15, s15, 7
	s_add_u32 s12, s12, s15
	s_lshl_b32 s15, s2, 7
	s_add_u32 s12, s12, s15
	s_add_u32 s12, s12, 0x12174000
	s_add_u32 s64, s8, s12
	s_addc_u32 s65, s9, 0
	v_lshlrev_b32_e32 v168, 7, v228
	v_lshl_add_u32 v168, v226, 3, v168
	v_add_u32_e32 v170, 0x4000, v168
	v_cvt_pk_bf16_f32 v138, v126, v118
	v_cvt_pk_bf16_f32 v139, v110, v102
	global_store_dwordx2 v168, v[138:139], s[64:65]
	v_cvt_pk_bf16_f32 v140, v127, v119
	v_cvt_pk_bf16_f32 v141, v111, v103
	global_store_dwordx2 v168, v[140:141], s[64:65] offset:128
	v_cvt_pk_bf16_f32 v142, v128, v120
	v_cvt_pk_bf16_f32 v143, v112, v104
	global_store_dwordx2 v168, v[142:143], s[64:65] offset:256
	v_cvt_pk_bf16_f32 v144, v129, v121
	v_cvt_pk_bf16_f32 v145, v113, v105
	global_store_dwordx2 v168, v[144:145], s[64:65] offset:384
	v_cvt_pk_bf16_f32 v146, v122, v114
	v_cvt_pk_bf16_f32 v147, v106, v98
	global_store_dwordx2 v168, v[146:147], s[64:65] offset:2048
	v_cvt_pk_bf16_f32 v148, v123, v115
	v_cvt_pk_bf16_f32 v149, v107, v99
	global_store_dwordx2 v168, v[148:149], s[64:65] offset:2176
	v_cvt_pk_bf16_f32 v150, v124, v116
	v_cvt_pk_bf16_f32 v151, v108, v100
	global_store_dwordx2 v168, v[150:151], s[64:65] offset:2304
	v_cvt_pk_bf16_f32 v152, v125, v117
	v_cvt_pk_bf16_f32 v153, v109, v101
	global_store_dwordx2 v168, v[152:153], s[64:65] offset:2432
	v_cvt_pk_bf16_f32 v138, v94, v86
	v_cvt_pk_bf16_f32 v139, v78, v70
	global_store_dwordx2 v170, v[138:139], s[64:65]
	v_cvt_pk_bf16_f32 v140, v95, v87
	v_cvt_pk_bf16_f32 v141, v79, v71
	global_store_dwordx2 v170, v[140:141], s[64:65] offset:128
	v_cvt_pk_bf16_f32 v142, v96, v88
	v_cvt_pk_bf16_f32 v143, v80, v72
	global_store_dwordx2 v170, v[142:143], s[64:65] offset:256
	v_cvt_pk_bf16_f32 v144, v97, v89
	v_cvt_pk_bf16_f32 v145, v81, v73
	global_store_dwordx2 v170, v[144:145], s[64:65] offset:384
	v_cvt_pk_bf16_f32 v146, v90, v82
	v_cvt_pk_bf16_f32 v147, v74, v66
	global_store_dwordx2 v170, v[146:147], s[64:65] offset:2048
	v_cvt_pk_bf16_f32 v148, v91, v83
	v_cvt_pk_bf16_f32 v149, v75, v67
	global_store_dwordx2 v170, v[148:149], s[64:65] offset:2176
	v_cvt_pk_bf16_f32 v150, v92, v84
	v_cvt_pk_bf16_f32 v151, v76, v68
	global_store_dwordx2 v170, v[150:151], s[64:65] offset:2304
	v_cvt_pk_bf16_f32 v152, v93, v85
	v_cvt_pk_bf16_f32 v153, v77, v69
	global_store_dwordx2 v170, v[152:153], s[64:65] offset:2432
	s_branch .Lip0_end

.Lip1_V:
	s_cmpk_lt_u32 s0, 0x180
	s_cbranch_scc0 .Lip1_RV
	s_lshr_b32 s12, s0, 6
	s_mul_i32 s12, s12, 0x208000
	s_and_b32 s15, s0, 63
	s_lshl_b32 s15, s15, 7
	s_add_u32 s12, s12, s15
	s_lshl_b32 s15, s2, 7
	s_add_u32 s12, s12, s15
	s_add_u32 s12, s12, 0x12174000
	s_add_u32 s64, s8, s12
	s_addc_u32 s65, s9, 0
	v_lshlrev_b32_e32 v168, 7, v228
	v_lshl_add_u32 v168, v226, 3, v168
	v_add_u32_e32 v170, 0x4000, v168
	v_cvt_pk_bf16_f32 v138, v62, v54
	v_cvt_pk_bf16_f32 v139, v46, v38
	global_store_dwordx2 v168, v[138:139], s[64:65]
	v_cvt_pk_bf16_f32 v140, v63, v55
	v_cvt_pk_bf16_f32 v141, v47, v39
	global_store_dwordx2 v168, v[140:141], s[64:65] offset:128
	v_cvt_pk_bf16_f32 v142, v64, v56
	v_cvt_pk_bf16_f32 v143, v48, v40
	global_store_dwordx2 v168, v[142:143], s[64:65] offset:256
	v_cvt_pk_bf16_f32 v144, v65, v57
	v_cvt_pk_bf16_f32 v145, v49, v41
	global_store_dwordx2 v168, v[144:145], s[64:65] offset:384
	v_cvt_pk_bf16_f32 v146, v58, v50
	v_cvt_pk_bf16_f32 v147, v42, v34
	global_store_dwordx2 v168, v[146:147], s[64:65] offset:2048
	v_cvt_pk_bf16_f32 v148, v59, v51
	v_cvt_pk_bf16_f32 v149, v43, v35
	global_store_dwordx2 v168, v[148:149], s[64:65] offset:2176
	v_cvt_pk_bf16_f32 v150, v60, v52
	v_cvt_pk_bf16_f32 v151, v44, v36
	global_store_dwordx2 v168, v[150:151], s[64:65] offset:2304
	v_cvt_pk_bf16_f32 v152, v61, v53
	v_cvt_pk_bf16_f32 v153, v45, v37
	global_store_dwordx2 v168, v[152:153], s[64:65] offset:2432
	v_cvt_pk_bf16_f32 v138, v30, v22
	v_cvt_pk_bf16_f32 v139, v14, v6
	global_store_dwordx2 v170, v[138:139], s[64:65]
	v_cvt_pk_bf16_f32 v140, v31, v23
	v_cvt_pk_bf16_f32 v141, v15, v7
	global_store_dwordx2 v170, v[140:141], s[64:65] offset:128
	v_cvt_pk_bf16_f32 v142, v32, v24
	v_cvt_pk_bf16_f32 v143, v16, v8
	global_store_dwordx2 v170, v[142:143], s[64:65] offset:256
	v_cvt_pk_bf16_f32 v144, v33, v25
	v_cvt_pk_bf16_f32 v145, v17, v9
	global_store_dwordx2 v170, v[144:145], s[64:65] offset:384
	v_cvt_pk_bf16_f32 v146, v26, v18
	v_cvt_pk_bf16_f32 v147, v10, v2
	global_store_dwordx2 v170, v[146:147], s[64:65] offset:2048
	v_cvt_pk_bf16_f32 v148, v27, v19
	v_cvt_pk_bf16_f32 v149, v11, v3
	global_store_dwordx2 v170, v[148:149], s[64:65] offset:2176
	v_cvt_pk_bf16_f32 v150, v28, v20
	v_cvt_pk_bf16_f32 v151, v12, v4
	global_store_dwordx2 v170, v[150:151], s[64:65] offset:2304
	v_cvt_pk_bf16_f32 v152, v29, v21
	v_cvt_pk_bf16_f32 v153, v13, v5
	global_store_dwordx2 v170, v[152:153], s[64:65] offset:2432
	s_branch .Lip1_end
